# phase 0a work rebalanced: workgroups 0-63 (SSM table items) stop after 6 items and their remaining weight-transpose tiles are spread over workgroups 64-255
# speedup vs baseline: 1.0049x; 1.0014x over previous
; DI int bidx() { int b = blockIdx.x; asm volatile("" : "+s"(b)); return b; }
; DI void phase0a(const Params& p, char* lds) {
;     ...
;   for (int it = bidx(); it < NITEMS; it += gridDim.x) {
;     if (it < N_SSM) { ssm_tables(p, it >> 1, it & 1, lds); continue; }
;     int i = it - N_SSM;
;     if (i < N_MOD) { mod_item(p, i, lds); continue; }
;     i -= N_MOD;
;     if (i < N_ROPE) {
;       float2* rope = (float2*)(p.ws + OFF_ROPE);
;       for (int e = tid; e < 4096; e += NT) {
;         const int pos = i * 512 + (e >> 3), f = e & 7;
;         const double invf = exp2(-(double)f * 0.125 * 18.931568569324174);
;         float s, c; sincos_rev((double)pos * invf, s, c);
;         rope[pos * 8 + f] = make_float2(c, s);
; __global__ void __launch_bounds__(NT) fwd_megakernel(Params p) {
;   __shared__ __attribute__((aligned(16))) char lds[LDS_BYTES];
;   cg::grid_group grid = cg::this_grid();
;   phase0a(p, lds);
_Z14fwd_megakernel6Params:
	s_add_u32 s4, s0, 0x130
	s_addc_u32 s5, s1, 0
	v_and_b32_e32 v162, 0x3ff, v0
	v_writelane_b32 v254, s4, 0
	v_mov_b32_e32 v1, v162
	s_mov_b32 s74, s2
	v_writelane_b32 v254, s5, 1
	v_writelane_b32 v254, s0, 2
	s_load_dword s12, s[0:1], 0x130
	s_cmpk_gt_i32 s74, 0x11a0
	v_writelane_b32 v254, s1, 3
	v_writelane_b32 v254, s2, 4
	s_waitcnt lgkmcnt(0)
	s_mov_b32 s20, 0
	v_writelane_b32 v255, s20, 52
	v_writelane_b32 v254, s12, 5
	s_cbranch_scc1 .LBB0_91
	s_movk_i32 s0, 0x1000
	v_and_b32_e32 v58, 7, v1
	v_cmp_gt_i32_e64 s[4:5], s0, v1
	v_cvt_f64_u32_e32 v[2:3], v58
	s_mov_b32 s0, 0x471b3a95
	v_ldexp_f64 v[2:3], -v[2:3], -3
	s_mov_b32 s1, 0x4032ee7b
	v_mul_f64 v[20:21], v[2:3], s[0:1]
	v_rndne_f64_e32 v[22:23], v[20:21]
	v_add_f64 v[2:3], v[20:21], -v[22:23]
	s_mov_b32 s45, 0x3c7abc9e
	s_mov_b32 s44, 0x3b39803f
	v_mul_f64 v[24:25], v[2:3], s[44:45]
	s_mov_b32 s47, 0x3fe62e42
	s_mov_b32 s46, 0xfefa39ef
	v_fmac_f64_e32 v[24:25], s[46:47], v[2:3]
	v_mov_b32_e32 v2, 0xfca7ab0c
	v_mov_b32_e32 v3, 0x3e928af3
	s_mov_b32 s48, 0x6a5dcb37
	s_mov_b32 s49, 0x3e5ade15
	v_mov_b64_e32 v[6:7], v[2:3]
	v_mov_b32_e32 v4, 0x623fde64
	v_mov_b32_e32 v5, 0x3ec71dee
	v_fmac_f64_e32 v[6:7], s[48:49], v[24:25]
	v_mov_b64_e32 v[8:9], v[4:5]
	v_fmac_f64_e32 v[8:9], v[24:25], v[6:7]
	v_mov_b32_e32 v6, 0x7c89e6b0
	v_mov_b32_e32 v7, 0x3efa0199
	v_mov_b64_e32 v[10:11], v[6:7]
	v_fmac_f64_e32 v[10:11], v[24:25], v[8:9]
	v_mov_b32_e32 v8, 0x14761f6e
	v_mov_b32_e32 v9, 0x3f2a01a0
	v_mov_b64_e32 v[12:13], v[8:9]
	v_fmac_f64_e32 v[12:13], v[24:25], v[10:11]
	v_mov_b32_e32 v10, 0x1852b7b0
	v_mov_b32_e32 v11, 0x3f56c16c
	v_mov_b64_e32 v[14:15], v[10:11]
	v_fmac_f64_e32 v[14:15], v[24:25], v[12:13]
	v_mov_b32_e32 v12, 0x11122322
	v_mov_b32_e32 v13, 0x3f811111
	v_mov_b64_e32 v[16:17], v[12:13]
	v_fmac_f64_e32 v[16:17], v[24:25], v[14:15]
	v_mov_b32_e32 v14, 0x555502a1
	v_mov_b32_e32 v15, 0x3fa55555
	v_mov_b64_e32 v[18:19], v[14:15]
	v_fmac_f64_e32 v[18:19], v[24:25], v[16:17]
	v_mov_b32_e32 v16, 0x55555511
	v_mov_b32_e32 v17, 0x3fc55555
	v_mov_b64_e32 v[26:27], v[16:17]
	v_fmac_f64_e32 v[26:27], v[24:25], v[18:19]
	v_mov_b32_e32 v18, 11
	v_mov_b32_e32 v19, 0x3fe00000
	v_readlane_b32 s2, v254, 2
	v_mov_b64_e32 v[28:29], v[18:19]
	v_readlane_b32 s3, v254, 3
	v_fmac_f64_e32 v[28:29], v[24:25], v[26:27]
	s_load_dwordx2 s[54:55], s[2:3], 0x128
	s_load_dwordx2 s[0:1], s[2:3], 0x118
	v_fma_f64 v[26:27], v[24:25], v[28:29], 1.0
	s_mov_b32 s50, 0
	s_mov_b32 s52, 0
	v_fma_f64 v[24:25], v[24:25], v[26:27], 1.0
	v_cvt_i32_f64_e32 v22, v[22:23]
	s_mov_b32 s51, 0x40900000
	s_mov_b32 s53, 0xc090cc00
	v_ldexp_f64 v[22:23], v[24:25], v22
	v_mov_b32_e32 v59, 0x7ff00000
	v_cmp_nlt_f64_e32 vcc, s[50:51], v[20:21]
	v_cmp_ngt_f64_e64 s[8:9], s[52:53], v[20:21]
	s_waitcnt lgkmcnt(0)
	v_writelane_b32 v254, s0, 6
	v_cndmask_b32_e32 v23, v59, v23, vcc
	s_and_b64 vcc, s[8:9], vcc
	s_add_u32 s33, s54, 0x1880000
	v_writelane_b32 v254, s1, 7
	s_addc_u32 s0, s55, 0
	v_writelane_b32 v254, s0, 8
	s_add_u32 s0, s54, 0x1080000
	v_writelane_b32 v254, s0, 9
	s_addc_u32 s0, s55, 0
	v_writelane_b32 v254, s0, 10
	s_add_u32 s0, s54, 0xe80000
	v_writelane_b32 v254, s0, 11
	s_addc_u32 s0, s55, 0
	v_writelane_b32 v254, s0, 12
	s_load_dwordx2 s[0:1], s[2:3], 0xe8
	s_load_dwordx2 s[92:93], s[2:3], 0x70
	s_load_dwordx4 s[28:31], s[2:3], 0xd0
	s_load_dwordx8 s[20:27], s[2:3], 0xf8
	s_mov_b32 s66, 0x6dc9c883
	s_mov_b32 s68, 0x652b82fe
	s_mov_b32 s6, 0x54442d18
	s_waitcnt lgkmcnt(0)
	v_writelane_b32 v254, s0, 14
	s_mov_b32 s60, 0x33145c00
	s_mov_b32 s88, 0x46cc5e42
	v_writelane_b32 v254, s1, 15
	s_add_u32 s0, s54, 0xe00000
	v_writelane_b32 v254, s0, 16
	s_addc_u32 s0, s55, 0
	v_writelane_b32 v254, s0, 18
	s_add_u32 s0, s54, 0xd00000
	v_writelane_b32 v254, s0, 19
	s_addc_u32 s0, s55, 0
	v_writelane_b32 v254, s0, 20
	s_add_u32 s0, s54, 0xb00000
	v_writelane_b32 v254, s0, 22
	s_addc_u32 s0, s55, 0
	v_writelane_b32 v254, s0, 24
	v_writelane_b32 v254, s20, 26
	s_add_u32 s86, s54, 0x43a4000
	s_addc_u32 s87, s55, 0
	v_writelane_b32 v254, s21, 27
	v_writelane_b32 v254, s22, 28
	v_writelane_b32 v254, s23, 29
	s_add_u32 s62, s54, 0x42a4000
	v_writelane_b32 v254, s24, 30
	s_addc_u32 s63, s55, 0
	v_writelane_b32 v254, s25, 31
	s_add_u32 s64, s54, 0x4280000
	v_writelane_b32 v254, s26, 32
	s_addc_u32 s65, s55, 0
	v_writelane_b32 v254, s27, 33
	s_load_dwordx8 s[20:27], s[2:3], 0x50
	s_load_dwordx8 s[36:43], s[2:3], 0x10
	s_add_u32 s12, s54, 0x4080000
	s_addc_u32 s13, s55, 0
	s_add_u32 s14, s54, 0x2080000
	s_mul_i32 s0, s74, 24
	s_mov_b32 s90, 0x55555555
	s_mov_b32 s80, 0xf9a43bb8
	s_mov_b32 s35, 0
	v_cmp_eq_u32_e64 s[84:85], 0, v1
	v_cndmask_b32_e64 v21, 0, v23, s[8:9]
	v_cndmask_b32_e32 v20, 0, v22, vcc
	s_addc_u32 s15, s55, 0
	s_add_i32 s34, s0, 0xfffffa00
	v_mov_b32_e32 v23, 0
	s_movk_i32 s17, 0x5800
	s_mov_b32 s67, 0x3fc45f30
	s_movk_i32 s59, 0x1800
	s_movk_i32 s18, 0x400
	s_movk_i32 s19, 0x6000
	s_mov_b32 s69, 0x3ff71547
	s_mov_b32 s47, 0xbfe62e42
	s_mov_b32 s45, 0xbc7abc9e
	s_mov_b32 s7, 0xbff921fb
	s_mov_b32 s61, 0xbc91a626
	s_mov_b32 s89, 0xbda907db
	s_mov_b32 s91, 0xbfc55555
	s_mov_b32 s81, 0x3de5e0b2
	s_brev_b32 s58, 1
	s_movk_i32 s16, 0x7dff
	v_mov_b32_e32 v60, 0x7f800000
	v_mov_b32_e32 v61, 0x40100000
	v_mov_b32_e32 v62, 0x3ff00000
	v_mov_b32_e32 v24, 0x9037ab78
	v_mov_b32_e32 v25, 0x3e21eeb6
	v_mov_b32_e32 v26, 0xa17f65f6
	v_mov_b32_e32 v27, 0xbe927e4f
	v_mov_b32_e32 v28, 0x19f4ec90
	v_mov_b32_e32 v29, 0x3efa01a0
	v_mov_b32_e32 v30, 0x16c16967
	v_mov_b32_e32 v31, 0xbf56c16c
	v_mov_b32_e32 v32, 0x55555555
	v_mov_b32_e32 v34, 0xb42fdfa7
	v_mov_b32_e32 v35, 0xbe5ae600
	v_mov_b32_e32 v36, 0x796cde01
	v_mov_b32_e32 v37, 0x3ec71de3
	v_mov_b32_e32 v38, 0x19e83e5c
	v_mov_b32_e32 v39, 0xbf2a01a0
	v_mov_b32_e32 v40, 0x11110bb3
	v_mov_b32_e32 v63, 0x7ff80000
	v_mov_b32_e32 v64, 0x4200
	s_mov_b64 s[82:83], 0x180000
	s_mov_b32 s71, 0x3ff921fb
	s_mov_b32 s73, 0x3c91a626
	s_mov_b32 s78, 0x33145c07
	s_mov_b32 s77, 0x3fe45f30
	s_branch .LBB0_4

; DI int bidx() { int b = blockIdx.x; asm volatile("" : "+s"(b)); return b; }
; DI void phase0a(const Params& p, char* lds) {
;     ...
;   for (int it = bidx(); it < NITEMS; it += gridDim.x) {
;     if (it < N_SSM) { ssm_tables(p, it >> 1, it & 1, lds); continue; }
.LBB0_3:
	v_readlane_b32 s0, v254, 5
	v_readlane_b32 vcc_lo, v255, 52
	v_readlane_b32 s8, v254, 4
	s_nop 3
	s_cmpk_lg_u32 s0, 0x100
	s_cbranch_scc1 .Lp0_orig
	s_cmp_lg_u32 vcc_lo, 0
	s_cbranch_scc1 .Lp0_extra_next
	s_add_i32 s74, s74, s0
	s_mul_i32 s9, s0, 24
	s_add_i32 s34, s34, s9
	s_cmp_lt_u32 s8, 64
	s_cbranch_scc0 .Lp0_big
	s_cmpk_lt_i32 s74, 0x600
	s_cbranch_scc1 .LBB0_4
	s_branch .LBB0_90
.Lp0_big:
	s_cmpk_lt_i32 s74, 0x11a1
	s_cbranch_scc1 .LBB0_4
	s_sub_i32 vcc_lo, s8, 64
	s_branch .Lp0_extra_set
.Lp0_extra_next:
	s_add_i32 vcc_lo, vcc_lo, 191
.Lp0_extra_set:
	s_cmpk_lt_i32 vcc_lo, 0x300
	s_cbranch_scc0 .LBB0_90
	s_add_i32 s9, vcc_lo, 1
	v_writelane_b32 v255, s9, 52
	s_and_b32 s9, vcc_lo, 63
	s_lshr_b32 vcc_lo, vcc_lo, 6
	s_add_i32 vcc_lo, vcc_lo, 6
	s_lshl_b32 vcc_lo, vcc_lo, 8
	s_add_i32 s74, vcc_lo, s9
	s_branch .LBB0_4
